# GDN chunk-prep phase: unit id bits [2:0]<->[5:3] swapped so all 8 waves of a workgroup process the same head (conv-weight scalar loads share the scalar cache)
# baseline (speedup 1.0000x reference)
; #define LAS __attribute__((address_space(3)))
; DI float bf2f(bf16 h) { return __uint_as_float(((unsigned)h) << 16); }
; DI void gdn_prep_unit(int uid, const bf16* qkv, const bf16* psmall, const float* convw, const float* a_log, const float* dt_bias,
;                       unsigned char* G, float* glast, LAS unsigned char* wl, int lane) {
;     ...
;     asm volatile("" : "+s"(uid));
;     const int h = uid & 7, n = (uid >> 3) & 63, b = uid >> 9;
;     const int row0 = b * T + 64 * n;
;     const int r32 = lane & 31, hi = lane >> 5;
;     unsigned char* Gu = G + (size_t)uid * 40960;
;     bf16* Wn = (bf16*)Gu; bf16* QD = Wn + 4096; bf16* AT = QD + 4096; bf16* KDT = AT + 4096; bf16* UT = KDT + 4096;
;     LAS unsigned char* R0 = wl; LAS unsigned char* R1 = wl + 9216; LAS unsigned char* HX = wl + 18432;
;     const bf16* pr = psmall + (size_t)(row0 + lane) * 1024;
;     const float xa = bf2f(pr[928 + h]) + dt_bias[h], xb = bf2f(pr[936 + h]);
;     const float sp = xa > 20.f ? xa : log1pf(__expf(xa));
;     const float g = -__expf(a_log[h]) * sp;
.LBB0_621:
	v_mov_b32_e32 v146, v196
	s_mov_b32 s78, s80
	s_and_b32 s0, s78, 7
	s_bfe_u32 s1, s78, 0x30003
	s_and_b32 s78, s78, 0xffffffc0
	s_lshl_b32 s0, s0, 3
	s_or_b32 s78, s78, s0
	s_or_b32 s78, s78, s1
	s_bfe_u32 s2, s78, 0x60003
	s_lshl_b32 s0, s78, 3
	s_and_b32 s0, s0, 0xfffff000
	s_lshl_b32 s1, s2, 6
	s_or_b32 s4, s1, s0
	v_add_u32_e32 v0, s4, v146
	s_waitcnt lgkmcnt(0)
	v_ashrrev_i32_e32 v1, 31, v0
	v_readlane_b32 s0, v253, 47
	s_and_b32 s3, s78, 7
	v_lshlrev_b64 v[0:1], 11, v[0:1]
	v_readlane_b32 s1, v253, 48
	s_lshl_b32 s76, s3, 1
	s_lshl_b32 s5, s3, 2
	v_lshl_add_u64 v[0:1], s[0:1], 0, v[0:1]
	v_lshl_add_u64 v[0:1], v[0:1], 0, s[76:77]
	global_load_ushort v2, v[0:1], off offset:1856
	v_readlane_b32 s8, v253, 21
	v_mov_b32_e32 v3, s5
	v_readlane_b32 s9, v253, 22
	s_nop 4
	global_load_dword v3, v3, s[8:9]
	s_nop 0
	global_load_ushort v1, v[0:1], off offset:1872
	s_mov_b32 s0, 0x41a00000
	v_readlane_b32 s10, v253, 23
	v_readlane_b32 s11, v253, 24
	v_readlane_b32 s12, v253, 25
	v_readlane_b32 s13, v253, 26
	v_readlane_b32 s14, v253, 27
	v_readlane_b32 s15, v253, 28
	v_readlane_b32 s16, v253, 29
	v_readlane_b32 s17, v253, 30
	v_readlane_b32 s18, v253, 31
	v_readlane_b32 s19, v253, 32
	v_readlane_b32 s20, v253, 33
	v_readlane_b32 s21, v253, 34
	v_readlane_b32 s22, v253, 35
	v_readlane_b32 s23, v253, 36
	s_waitcnt vmcnt(0)
	v_lshlrev_b32_e32 v0, 16, v2
	v_add_f32_e32 v0, v3, v0
	v_cmp_nlt_f32_e32 vcc, s0, v0
	s_and_saveexec_b64 s[0:1], vcc
	s_cbranch_execz .LBB0_623
	v_mul_f32_e32 v0, 0x3fb8aa3b, v0
	v_exp_f32_e32 v0, v0
	s_mov_b32 s6, 0x3f2aaaab
	v_add_f32_e32 v4, 1.0, v0
	v_frexp_mant_f32_e32 v6, v4
	v_cvt_f64_f32_e32 v[2:3], v4
	v_frexp_exp_i32_f64_e32 v2, v[2:3]
	v_cmp_gt_f32_e32 vcc, s6, v6
	v_add_f32_e32 v5, -1.0, v4
	v_sub_f32_e32 v7, v5, v4
	v_subbrev_co_u32_e32 v10, vcc, 0, v2, vcc
	v_sub_u32_e32 v2, 0, v10
	v_sub_f32_e32 v5, v0, v5
	v_add_f32_e32 v7, 1.0, v7
	v_ldexp_f32 v3, v4, v2
	v_add_f32_e32 v5, v5, v7
	v_add_f32_e32 v4, -1.0, v3
	v_add_f32_e32 v6, 1.0, v3
	v_ldexp_f32 v2, v5, v2
	v_add_f32_e32 v5, 1.0, v4
	v_add_f32_e32 v7, -1.0, v6
	v_sub_f32_e32 v5, v3, v5
	v_sub_f32_e32 v3, v3, v7
	v_add_f32_e32 v5, v2, v5
	v_add_f32_e32 v2, v2, v3
	v_add_f32_e32 v11, v6, v2
	v_rcp_f32_e32 v13, v11
	v_sub_f32_e32 v3, v11, v6
	v_sub_f32_e32 v12, v2, v3
	v_add_f32_e32 v3, v4, v5
	v_mul_f32_e32 v15, v3, v13
	v_sub_f32_e32 v2, v3, v4
	v_mul_f32_e32 v4, v11, v15
	v_fma_f32 v6, v15, v11, -v4
	v_fmac_f32_e32 v6, v15, v12
	v_sub_f32_e32 v14, v5, v2
	v_add_f32_e32 v2, v4, v6
	v_sub_f32_e32 v5, v3, v2
	v_pk_add_f32 v[8:9], v[2:3], v[4:5] neg_lo:[0,1] neg_hi:[0,1]
	v_mov_b32_e32 v7, v2
	v_pk_add_f32 v[2:3], v[8:9], v[6:7] neg_lo:[0,1] neg_hi:[0,1]
	s_mov_b32 s6, 0x3f317218
	v_add_f32_e32 v3, v14, v3
	v_add_f32_e32 v2, v2, v3
	v_add_f32_e32 v3, v5, v2
	v_mul_f32_e32 v14, v13, v3
	v_mul_f32_e32 v4, v11, v14
	v_fma_f32 v6, v14, v11, -v4
	v_fmac_f32_e32 v6, v14, v12
	v_sub_f32_e32 v5, v5, v3
	v_add_f32_e32 v11, v2, v5
	v_add_f32_e32 v2, v4, v6
	v_sub_f32_e32 v5, v3, v2
	v_pk_add_f32 v[8:9], v[2:3], v[4:5] neg_lo:[0,1] neg_hi:[0,1]
	v_mov_b32_e32 v7, v2
	v_pk_add_f32 v[2:3], v[8:9], v[6:7] neg_lo:[0,1] neg_hi:[0,1]
	s_nop 0
	v_add_f32_e32 v3, v11, v3
	v_add_f32_e32 v2, v2, v3
	v_add_f32_e32 v3, v15, v14
	v_add_f32_e32 v2, v5, v2
	v_sub_f32_e32 v4, v3, v15
	v_mul_f32_e32 v2, v13, v2
	v_sub_f32_e32 v4, v14, v4
	v_add_f32_e32 v4, v4, v2
	v_add_f32_e32 v6, v3, v4
	v_mul_f32_e32 v7, v6, v6
	v_fmamk_f32 v2, v7, 0x3e9b6dac, v134
	v_fmaak_f32 v91, v7, v2, 0x3f2aaada
	v_cvt_f32_i32_e32 v2, v10
	v_sub_f32_e32 v3, v6, v3
	v_sub_f32_e32 v3, v4, v3
	v_ldexp_f32 v8, v3, 1
	v_mul_f32_e32 v3, v6, v7
	v_ldexp_f32 v5, v6, 1
	v_pk_mul_f32 v[6:7], v[2:3], v[90:91]
	s_nop 0
	v_fma_f32 v4, v2, s6, -v6
	v_fmac_f32_e32 v4, 0xb102e308, v2
	v_pk_add_f32 v[2:3], v[6:7], v[4:5]
	s_mov_b32 s6, 0x7f800000
	v_sub_f32_e32 v5, v3, v5
	v_sub_f32_e32 v5, v7, v5
	v_add_f32_e32 v9, v8, v5
	v_mov_b32_e32 v8, v6
	v_pk_add_f32 v[6:7], v[2:3], v[6:7] neg_lo:[0,1] neg_hi:[0,1]
	v_pk_add_f32 v[10:11], v[2:3], v[8:9]
	v_mov_b32_e32 v5, v2
	v_mov_b32_e32 v7, v11
	v_pk_add_f32 v[12:13], v[4:5], v[6:7] neg_lo:[0,1] neg_hi:[0,1]
	v_pk_add_f32 v[4:5], v[4:5], v[6:7]
	v_mov_b32_e32 v8, v9
	v_pk_add_f32 v[6:7], v[4:5], v[2:3] op_sel:[1,0] op_sel_hi:[0,1] neg_lo:[0,1] neg_hi:[0,1]
	v_pk_add_f32 v[14:15], v[10:11], v[6:7] op_sel_hi:[1,0] neg_lo:[0,1] neg_hi:[0,1]
	v_mov_b32_e32 v10, v11
	v_mov_b32_e32 v11, v5
	v_pk_mov_b32 v[6:7], v[2:3], v[6:7] op_sel:[1,0]
	v_mov_b32_e32 v9, v2
	v_pk_add_f32 v[6:7], v[10:11], v[6:7] neg_lo:[0,1] neg_hi:[0,1]
	v_mov_b32_e32 v14, v12
	v_pk_add_f32 v[2:3], v[8:9], v[6:7] neg_lo:[0,1] neg_hi:[0,1]
	v_mov_b32_e32 v13, v5
	v_pk_add_f32 v[6:7], v[14:15], v[2:3]
	v_cmp_neq_f32_e32 vcc, s6, v0
	v_pk_add_f32 v[8:9], v[6:7], v[6:7] op_sel:[0,1] op_sel_hi:[1,0]
	s_mov_b32 s6, 0x33800000
	v_pk_add_f32 v[4:5], v[4:5], v[8:9] op_sel:[1,0] op_sel_hi:[0,1]
	v_mov_b32_e32 v7, v4
	v_pk_add_f32 v[10:11], v[6:7], v[12:13] neg_lo:[0,1] neg_hi:[0,1]
	v_mov_b32_e32 v3, v8
	v_sub_f32_e32 v5, v6, v10
	v_pk_add_f32 v[2:3], v[2:3], v[10:11] neg_lo:[0,1] neg_hi:[0,1]
	v_sub_f32_e32 v5, v12, v5
	v_add_f32_e32 v2, v2, v5
	v_add_f32_e32 v2, v2, v3
	v_add_f32_e32 v2, v4, v2
	v_cndmask_b32_e32 v2, v137, v2, vcc
	v_cmp_ngt_f32_e32 vcc, -1.0, v0
	s_nop 1
	v_cndmask_b32_e32 v2, v138, v2, vcc
	v_cmp_neq_f32_e32 vcc, -1.0, v0
	s_nop 1
	v_cndmask_b32_e32 v2, v139, v2, vcc
	v_cmp_lt_f32_e64 vcc, |v0|, s6
	s_nop 1
	v_cndmask_b32_e32 v0, v2, v0, vcc
